# attention finish(): 32 gate words preloaded up front, counted vmcnt(31) instead of 32 dependent load/vmcnt(0)/store round trips (3 instances)
# speedup vs baseline: 1.0188x; 1.0188x over previous
.LBB0_1021:
	s_and_saveexec_b64 s[48:49], s[44:45]
	ds_write_b32 v181, v81
	s_or_b64 exec, exec, s[48:49]
	s_waitcnt lgkmcnt(0)
	v_lshl_add_u32 v68, v167, 4, s41
	ds_read_b128 v[70:73], v68
	s_ashr_i32 s47, s46, 31
	s_lshl_b64 s[16:17], s[46:47], 11
	v_readlane_b32 s1, v253, 51
	s_add_u32 s1, s1, s16
	v_readlane_b32 s9, v253, 52
	s_waitcnt lgkmcnt(0)
	v_rcp_f32_e32 v69, v70
	v_rcp_f32_e32 v70, v71
	s_addc_u32 s9, s9, s17
	s_add_u32 s1, s1, s78
	v_and_b32_e32 v1, 1, v164
	s_addc_u32 s9, s9, 0
	s_lshl_b32 s13, s36, 1
	v_cmp_eq_u32_e32 vcc, 0, v1
	v_and_b32_e32 v2, 30, v164
	v_lshlrev_b32_e32 v71, 12, v167
	v_lshlrev_b32_e32 v1, 10, v1
	s_add_u32 s44, s1, s13
	v_or3_b32 v1, v71, v1, v2
	v_mul_f32_e32 v2, v52, v69
	v_mul_f32_e32 v52, v53, v70
	s_addc_u32 s45, s9, 0
	v_readlane_b32 s1, v253, 53
	v_cndmask_b32_e32 v53, v2, v52, vcc
	s_add_u32 s1, s1, s16
	v_readlane_b32 s9, v253, 54
	ds_bpermute_b32 v53, v212, v53
	s_addc_u32 s9, s9, s17
	s_add_u32 s1, s1, s78
	s_addc_u32 s9, s9, 0
	s_add_u32 s46, s1, s13
	s_addc_u32 s47, s9, 0
	s_waitcnt lgkmcnt(0)
	v_cndmask_b32_e32 v71, v53, v2, vcc
	v_lshlrev_b32_e32 v2, 1, v1
	v_or_b32_e32 v74, 0x1000, v2
	v_or_b32_e32 v75, 0x4000, v2
	v_or_b32_e32 v76, 0x5000, v2
	v_or_b32_e32 v77, 0x8000, v2
	v_or_b32_e32 v78, 0x9000, v2
	v_or_b32_e32 v79, 0xc000, v2
	v_or_b32_e32 v80, 0xd000, v2
	global_load_dword v81, v2, s[46:47]
	global_load_dword v82, v2, s[46:47] offset:64
	global_load_dword v83, v2, s[46:47] offset:128
	global_load_dword v84, v2, s[46:47] offset:192
	global_load_dword v85, v74, s[46:47]
	global_load_dword v86, v74, s[46:47] offset:64
	global_load_dword v87, v74, s[46:47] offset:128
	global_load_dword v88, v74, s[46:47] offset:192
	global_load_dword v89, v75, s[46:47]
	global_load_dword v90, v75, s[46:47] offset:64
	global_load_dword v91, v75, s[46:47] offset:128
	global_load_dword v92, v75, s[46:47] offset:192
	global_load_dword v93, v76, s[46:47]
	global_load_dword v94, v76, s[46:47] offset:64
	global_load_dword v95, v76, s[46:47] offset:128
	global_load_dword v96, v76, s[46:47] offset:192
	global_load_dword v97, v77, s[46:47]
	global_load_dword v98, v77, s[46:47] offset:64
	global_load_dword v99, v77, s[46:47] offset:128
	global_load_dword v100, v77, s[46:47] offset:192
	global_load_dword v101, v78, s[46:47]
	global_load_dword v102, v78, s[46:47] offset:64
	global_load_dword v103, v78, s[46:47] offset:128
	global_load_dword v104, v78, s[46:47] offset:192
	global_load_dword v105, v79, s[46:47]
	global_load_dword v106, v79, s[46:47] offset:64
	global_load_dword v107, v79, s[46:47] offset:128
	global_load_dword v108, v79, s[46:47] offset:192
	global_load_dword v109, v80, s[46:47]
	global_load_dword v110, v80, s[46:47] offset:64
	global_load_dword v111, v80, s[46:47] offset:128
	global_load_dword v112, v80, s[46:47] offset:192
	s_nop 0
	s_nop 0
	v_cndmask_b32_e32 v52, v52, v53, vcc
	s_waitcnt vmcnt(31)
	v_lshlrev_b32_e32 v53, 16, v81
	v_and_b32_e32 v1, 0xffff0000, v81
	v_mul_f32_e32 v53, v71, v53
	v_mul_f32_e32 v1, v52, v1
	v_cvt_pk_bf16_f32 v1, v53, v1
	global_store_dword v2, v1, s[44:45]
	v_mul_f32_e32 v1, v36, v69
	v_mul_f32_e32 v36, v37, v70
	v_cndmask_b32_e32 v37, v1, v36, vcc
	ds_bpermute_b32 v37, v212, v37
	s_waitcnt lgkmcnt(0)
	v_cndmask_b32_e32 v1, v37, v1, vcc
	v_cndmask_b32_e32 v36, v36, v37, vcc
	s_waitcnt vmcnt(31)
	v_lshlrev_b32_e32 v52, 16, v82
	v_and_b32_e32 v37, 0xffff0000, v82
	v_mul_f32_e32 v1, v1, v52
	v_mul_f32_e32 v36, v36, v37
	v_cvt_pk_bf16_f32 v1, v1, v36
	global_store_dword v2, v1, s[44:45] offset:64
	v_mul_f32_e32 v1, v20, v69
	v_mul_f32_e32 v20, v21, v70
	v_cndmask_b32_e32 v21, v1, v20, vcc
	ds_bpermute_b32 v21, v212, v21
	s_waitcnt lgkmcnt(0)
	v_cndmask_b32_e32 v1, v21, v1, vcc
	v_cndmask_b32_e32 v20, v20, v21, vcc
	s_waitcnt vmcnt(31)
	v_lshlrev_b32_e32 v36, 16, v83
	v_and_b32_e32 v21, 0xffff0000, v83
	v_mul_f32_e32 v1, v1, v36
	v_mul_f32_e32 v20, v20, v21
	v_cvt_pk_bf16_f32 v1, v1, v20
	global_store_dword v2, v1, s[44:45] offset:128
	v_mul_f32_e32 v1, v4, v69
	v_mul_f32_e32 v4, v5, v70
	v_cndmask_b32_e32 v5, v1, v4, vcc
	ds_bpermute_b32 v5, v212, v5
	s_waitcnt lgkmcnt(0)
	v_cndmask_b32_e32 v1, v5, v1, vcc
	v_cndmask_b32_e32 v4, v4, v5, vcc
	s_waitcnt vmcnt(31)
	v_lshlrev_b32_e32 v20, 16, v84
	v_and_b32_e32 v5, 0xffff0000, v84
	v_mul_f32_e32 v1, v1, v20
	v_mul_f32_e32 v4, v4, v5
	v_cvt_pk_bf16_f32 v1, v1, v4
	global_store_dword v2, v1, s[44:45] offset:192
	v_rcp_f32_e32 v1, v72
	v_rcp_f32_e32 v4, v73
	v_mul_f32_e32 v5, v54, v1
	v_mul_f32_e32 v20, v55, v4
	v_cndmask_b32_e32 v21, v5, v20, vcc
	ds_bpermute_b32 v21, v212, v21
	s_waitcnt lgkmcnt(0)
	v_cndmask_b32_e32 v5, v21, v5, vcc
	v_cndmask_b32_e32 v20, v20, v21, vcc
	v_or_b32_e32 v21, 0x1000, v2
	s_waitcnt vmcnt(31)
	v_lshlrev_b32_e32 v37, 16, v85
	v_and_b32_e32 v36, 0xffff0000, v85
	v_mul_f32_e32 v5, v5, v37
	v_mul_f32_e32 v20, v20, v36
	v_cvt_pk_bf16_f32 v5, v5, v20
	global_store_dword v21, v5, s[44:45]
	v_mul_f32_e32 v5, v38, v1
	v_mul_f32_e32 v20, v39, v4
	v_cndmask_b32_e32 v36, v5, v20, vcc
	ds_bpermute_b32 v36, v212, v36
	s_waitcnt lgkmcnt(0)
	v_cndmask_b32_e32 v5, v36, v5, vcc
	v_cndmask_b32_e32 v20, v20, v36, vcc
	s_waitcnt vmcnt(31)
	v_lshlrev_b32_e32 v37, 16, v86
	v_and_b32_e32 v36, 0xffff0000, v86
	v_mul_f32_e32 v5, v5, v37
	v_mul_f32_e32 v20, v20, v36
	v_cvt_pk_bf16_f32 v5, v5, v20
	global_store_dword v21, v5, s[44:45] offset:64
	v_mul_f32_e32 v5, v22, v1
	v_mul_f32_e32 v20, v23, v4
	v_cndmask_b32_e32 v22, v5, v20, vcc
	ds_bpermute_b32 v22, v212, v22
	v_mul_f32_e32 v1, v6, v1
	v_mul_f32_e32 v4, v7, v4
	s_waitcnt lgkmcnt(0)
	v_cndmask_b32_e32 v5, v22, v5, vcc
	v_cndmask_b32_e32 v20, v20, v22, vcc
	s_waitcnt vmcnt(31)
	v_lshlrev_b32_e32 v23, 16, v87
	v_and_b32_e32 v22, 0xffff0000, v87
	v_mul_f32_e32 v5, v5, v23
	v_mul_f32_e32 v20, v20, v22
	v_cvt_pk_bf16_f32 v5, v5, v20
	global_store_dword v21, v5, s[44:45] offset:128
	v_cndmask_b32_e32 v5, v1, v4, vcc
	ds_bpermute_b32 v5, v212, v5
	s_waitcnt lgkmcnt(0)
	v_cndmask_b32_e32 v1, v5, v1, vcc
	v_cndmask_b32_e32 v4, v4, v5, vcc
	s_waitcnt vmcnt(31)
	v_lshlrev_b32_e32 v6, 16, v88
	v_and_b32_e32 v5, 0xffff0000, v88
	v_mul_f32_e32 v1, v1, v6
	v_mul_f32_e32 v4, v4, v5
	v_cvt_pk_bf16_f32 v1, v1, v4
	ds_read_b128 v[4:7], v68 offset:32
	global_store_dword v21, v1, s[44:45] offset:192
	s_waitcnt lgkmcnt(0)
	v_rcp_f32_e32 v4, v4
	v_rcp_f32_e32 v5, v5
	v_mul_f32_e32 v1, v56, v4
	v_mul_f32_e32 v20, v57, v5
	v_cndmask_b32_e32 v21, v1, v20, vcc
	ds_bpermute_b32 v21, v212, v21
	s_waitcnt lgkmcnt(0)
	v_cndmask_b32_e32 v1, v21, v1, vcc
	v_cndmask_b32_e32 v20, v20, v21, vcc
	v_or_b32_e32 v21, 0x4000, v2
	s_waitcnt vmcnt(31)
	v_lshlrev_b32_e32 v23, 16, v89
	v_and_b32_e32 v22, 0xffff0000, v89
	v_mul_f32_e32 v1, v1, v23
	v_mul_f32_e32 v20, v20, v22
	v_cvt_pk_bf16_f32 v1, v1, v20
	global_store_dword v21, v1, s[44:45]
	v_mul_f32_e32 v1, v40, v4
	v_mul_f32_e32 v20, v41, v5
	v_cndmask_b32_e32 v22, v1, v20, vcc
	ds_bpermute_b32 v22, v212, v22
	s_waitcnt lgkmcnt(0)
	v_cndmask_b32_e32 v1, v22, v1, vcc
	v_cndmask_b32_e32 v20, v20, v22, vcc
	s_waitcnt vmcnt(31)
	v_lshlrev_b32_e32 v23, 16, v90
	v_and_b32_e32 v22, 0xffff0000, v90
	v_mul_f32_e32 v1, v1, v23
	v_mul_f32_e32 v20, v20, v22
	v_cvt_pk_bf16_f32 v1, v1, v20
	global_store_dword v21, v1, s[44:45] offset:64
	v_mul_f32_e32 v1, v24, v4
	v_mul_f32_e32 v20, v25, v5
	v_cndmask_b32_e32 v22, v1, v20, vcc
	ds_bpermute_b32 v22, v212, v22
	s_waitcnt lgkmcnt(0)
	v_cndmask_b32_e32 v1, v22, v1, vcc
	v_cndmask_b32_e32 v20, v20, v22, vcc
	s_waitcnt vmcnt(31)
	v_lshlrev_b32_e32 v23, 16, v91
	v_and_b32_e32 v22, 0xffff0000, v91
	v_mul_f32_e32 v1, v1, v23
	v_mul_f32_e32 v20, v20, v22
	v_cvt_pk_bf16_f32 v1, v1, v20
	global_store_dword v21, v1, s[44:45] offset:128
	v_mul_f32_e32 v1, v8, v4
	v_mul_f32_e32 v4, v9, v5
	v_cndmask_b32_e32 v5, v1, v4, vcc
	ds_bpermute_b32 v5, v212, v5
	s_waitcnt lgkmcnt(0)
	v_cndmask_b32_e32 v1, v5, v1, vcc
	v_cndmask_b32_e32 v4, v4, v5, vcc
	s_waitcnt vmcnt(31)
	v_lshlrev_b32_e32 v8, 16, v92
	v_and_b32_e32 v5, 0xffff0000, v92
	v_mul_f32_e32 v1, v1, v8
	v_mul_f32_e32 v4, v4, v5
	v_cvt_pk_bf16_f32 v1, v1, v4
	global_store_dword v21, v1, s[44:45] offset:192
	v_rcp_f32_e32 v1, v6
	v_rcp_f32_e32 v4, v7
	v_mul_f32_e32 v5, v58, v1
	v_mul_f32_e32 v6, v59, v4
	v_cndmask_b32_e32 v7, v5, v6, vcc
	ds_bpermute_b32 v7, v212, v7
	s_waitcnt lgkmcnt(0)
	v_cndmask_b32_e32 v5, v7, v5, vcc
	v_cndmask_b32_e32 v6, v6, v7, vcc
	v_or_b32_e32 v7, 0x5000, v2
	s_waitcnt vmcnt(31)
	v_lshlrev_b32_e32 v9, 16, v93
	v_and_b32_e32 v8, 0xffff0000, v93
	v_mul_f32_e32 v5, v5, v9
	v_mul_f32_e32 v6, v6, v8
	v_cvt_pk_bf16_f32 v5, v5, v6
	global_store_dword v7, v5, s[44:45]
	v_mul_f32_e32 v5, v42, v1
	v_mul_f32_e32 v6, v43, v4
	v_cndmask_b32_e32 v8, v5, v6, vcc
	ds_bpermute_b32 v8, v212, v8
	s_waitcnt lgkmcnt(0)
	v_cndmask_b32_e32 v5, v8, v5, vcc
	v_cndmask_b32_e32 v6, v6, v8, vcc
	s_waitcnt vmcnt(31)
	v_lshlrev_b32_e32 v9, 16, v94
	v_and_b32_e32 v8, 0xffff0000, v94
	v_mul_f32_e32 v5, v5, v9
	v_mul_f32_e32 v6, v6, v8
	v_cvt_pk_bf16_f32 v5, v5, v6
	global_store_dword v7, v5, s[44:45] offset:64
	v_mul_f32_e32 v5, v26, v1
	v_mul_f32_e32 v6, v27, v4
	v_cndmask_b32_e32 v8, v5, v6, vcc
	ds_bpermute_b32 v8, v212, v8
	v_mul_f32_e32 v1, v10, v1
	v_mul_f32_e32 v4, v11, v4
	s_waitcnt lgkmcnt(0)
	v_cndmask_b32_e32 v5, v8, v5, vcc
	v_cndmask_b32_e32 v6, v6, v8, vcc
	s_waitcnt vmcnt(31)
	v_lshlrev_b32_e32 v9, 16, v95
	v_and_b32_e32 v8, 0xffff0000, v95
	v_mul_f32_e32 v5, v5, v9
	v_mul_f32_e32 v6, v6, v8
	v_cvt_pk_bf16_f32 v5, v5, v6
	global_store_dword v7, v5, s[44:45] offset:128
	v_cndmask_b32_e32 v5, v1, v4, vcc
	ds_bpermute_b32 v5, v212, v5
	s_waitcnt lgkmcnt(0)
	v_cndmask_b32_e32 v1, v5, v1, vcc
	v_cndmask_b32_e32 v4, v4, v5, vcc
	s_waitcnt vmcnt(31)
	v_lshlrev_b32_e32 v6, 16, v96
	v_and_b32_e32 v5, 0xffff0000, v96
	v_mul_f32_e32 v1, v1, v6
	v_mul_f32_e32 v4, v4, v5
	v_cvt_pk_bf16_f32 v1, v1, v4
	global_store_dword v7, v1, s[44:45] offset:192
	ds_read_b128 v[4:7], v68 offset:64
	s_waitcnt lgkmcnt(0)
	v_rcp_f32_e32 v1, v4
	v_rcp_f32_e32 v4, v5
	v_mul_f32_e32 v5, v60, v1
	v_mul_f32_e32 v8, v61, v4
	v_cndmask_b32_e32 v9, v5, v8, vcc
	ds_bpermute_b32 v9, v212, v9
	s_waitcnt lgkmcnt(0)
	v_cndmask_b32_e32 v5, v9, v5, vcc
	v_cndmask_b32_e32 v8, v8, v9, vcc
	v_or_b32_e32 v9, 0x8000, v2
	s_waitcnt vmcnt(31)
	v_lshlrev_b32_e32 v11, 16, v97
	v_and_b32_e32 v10, 0xffff0000, v97
	v_mul_f32_e32 v5, v5, v11
	v_mul_f32_e32 v8, v8, v10
	v_cvt_pk_bf16_f32 v5, v5, v8
	global_store_dword v9, v5, s[44:45]
	v_mul_f32_e32 v5, v44, v1
	v_mul_f32_e32 v8, v45, v4
	v_cndmask_b32_e32 v10, v5, v8, vcc
	ds_bpermute_b32 v10, v212, v10
	s_waitcnt lgkmcnt(0)
	v_cndmask_b32_e32 v5, v10, v5, vcc
	v_cndmask_b32_e32 v8, v8, v10, vcc
	s_waitcnt vmcnt(31)
	v_lshlrev_b32_e32 v11, 16, v98
	v_and_b32_e32 v10, 0xffff0000, v98
	v_mul_f32_e32 v5, v5, v11
	v_mul_f32_e32 v8, v8, v10
	v_cvt_pk_bf16_f32 v5, v5, v8
	global_store_dword v9, v5, s[44:45] offset:64
	v_mul_f32_e32 v5, v28, v1
	v_mul_f32_e32 v8, v29, v4
	v_cndmask_b32_e32 v10, v5, v8, vcc
	ds_bpermute_b32 v10, v212, v10
	v_mul_f32_e32 v1, v12, v1
	v_mul_f32_e32 v4, v13, v4
	s_waitcnt lgkmcnt(0)
	v_cndmask_b32_e32 v5, v10, v5, vcc
	v_cndmask_b32_e32 v8, v8, v10, vcc
	s_waitcnt vmcnt(31)
	v_lshlrev_b32_e32 v11, 16, v99
	v_and_b32_e32 v10, 0xffff0000, v99
	v_mul_f32_e32 v5, v5, v11
	v_mul_f32_e32 v8, v8, v10
	v_cvt_pk_bf16_f32 v5, v5, v8
	global_store_dword v9, v5, s[44:45] offset:128
	v_cndmask_b32_e32 v5, v1, v4, vcc
	ds_bpermute_b32 v5, v212, v5
	s_waitcnt lgkmcnt(0)
	v_cndmask_b32_e32 v1, v5, v1, vcc
	v_cndmask_b32_e32 v4, v4, v5, vcc
	s_waitcnt vmcnt(31)
	v_lshlrev_b32_e32 v8, 16, v100
	v_and_b32_e32 v5, 0xffff0000, v100
	v_mul_f32_e32 v1, v1, v8
	v_mul_f32_e32 v4, v4, v5
	v_cvt_pk_bf16_f32 v1, v1, v4
	global_store_dword v9, v1, s[44:45] offset:192
	v_rcp_f32_e32 v1, v6
	v_rcp_f32_e32 v4, v7
	v_mul_f32_e32 v5, v62, v1
	v_mul_f32_e32 v6, v63, v4
	v_cndmask_b32_e32 v7, v5, v6, vcc
	ds_bpermute_b32 v7, v212, v7
	s_waitcnt lgkmcnt(0)
	v_cndmask_b32_e32 v5, v7, v5, vcc
	v_cndmask_b32_e32 v6, v6, v7, vcc
	v_or_b32_e32 v7, 0x9000, v2
	s_waitcnt vmcnt(31)
	v_lshlrev_b32_e32 v9, 16, v101
	v_and_b32_e32 v8, 0xffff0000, v101
	v_mul_f32_e32 v5, v5, v9
	v_mul_f32_e32 v6, v6, v8
	v_cvt_pk_bf16_f32 v5, v5, v6
	global_store_dword v7, v5, s[44:45]
	v_mul_f32_e32 v5, v46, v1
	v_mul_f32_e32 v6, v47, v4
	v_cndmask_b32_e32 v8, v5, v6, vcc
	ds_bpermute_b32 v8, v212, v8
	s_waitcnt lgkmcnt(0)
	v_cndmask_b32_e32 v5, v8, v5, vcc
	v_cndmask_b32_e32 v6, v6, v8, vcc
	s_waitcnt vmcnt(31)
	v_lshlrev_b32_e32 v9, 16, v102
	v_and_b32_e32 v8, 0xffff0000, v102
	v_mul_f32_e32 v5, v5, v9
	v_mul_f32_e32 v6, v6, v8
	v_cvt_pk_bf16_f32 v5, v5, v6
	global_store_dword v7, v5, s[44:45] offset:64
	v_mul_f32_e32 v5, v30, v1
	v_mul_f32_e32 v6, v31, v4
	v_cndmask_b32_e32 v8, v5, v6, vcc
	ds_bpermute_b32 v8, v212, v8
	v_mul_f32_e32 v1, v14, v1
	v_mul_f32_e32 v4, v15, v4
	s_waitcnt lgkmcnt(0)
	v_cndmask_b32_e32 v5, v8, v5, vcc
	v_cndmask_b32_e32 v6, v6, v8, vcc
	s_waitcnt vmcnt(31)
	v_lshlrev_b32_e32 v9, 16, v103
	v_and_b32_e32 v8, 0xffff0000, v103
	v_mul_f32_e32 v5, v5, v9
	v_mul_f32_e32 v6, v6, v8
	v_cvt_pk_bf16_f32 v5, v5, v6
	global_store_dword v7, v5, s[44:45] offset:128
	v_cndmask_b32_e32 v5, v1, v4, vcc
	ds_bpermute_b32 v5, v212, v5
	s_waitcnt lgkmcnt(0)
	v_cndmask_b32_e32 v1, v5, v1, vcc
	v_cndmask_b32_e32 v4, v4, v5, vcc
	s_waitcnt vmcnt(31)
	v_lshlrev_b32_e32 v6, 16, v104
	v_and_b32_e32 v5, 0xffff0000, v104
	v_mul_f32_e32 v1, v1, v6
	v_mul_f32_e32 v4, v4, v5
	v_cvt_pk_bf16_f32 v1, v1, v4
	global_store_dword v7, v1, s[44:45] offset:192
	ds_read_b128 v[4:7], v68 offset:96
	s_waitcnt lgkmcnt(0)
	v_rcp_f32_e32 v4, v4
	v_rcp_f32_e32 v5, v5
	v_mul_f32_e32 v1, v64, v4
	v_mul_f32_e32 v8, v65, v5
	v_cndmask_b32_e32 v9, v1, v8, vcc
	ds_bpermute_b32 v9, v212, v9
	s_waitcnt lgkmcnt(0)
	v_cndmask_b32_e32 v1, v9, v1, vcc
	v_cndmask_b32_e32 v8, v8, v9, vcc
	v_or_b32_e32 v9, 0xc000, v2
	v_or_b32_e32 v2, 0xd000, v2
	s_waitcnt vmcnt(31)
	v_lshlrev_b32_e32 v11, 16, v105
	v_and_b32_e32 v10, 0xffff0000, v105
	v_mul_f32_e32 v1, v1, v11
	v_mul_f32_e32 v8, v8, v10
	v_cvt_pk_bf16_f32 v1, v1, v8
	global_store_dword v9, v1, s[44:45]
	v_mul_f32_e32 v1, v48, v4
	v_mul_f32_e32 v8, v49, v5
	v_cndmask_b32_e32 v10, v1, v8, vcc
	ds_bpermute_b32 v10, v212, v10
	s_waitcnt lgkmcnt(0)
	v_cndmask_b32_e32 v1, v10, v1, vcc
	v_cndmask_b32_e32 v8, v8, v10, vcc
	s_waitcnt vmcnt(31)
	v_lshlrev_b32_e32 v11, 16, v106
	v_and_b32_e32 v10, 0xffff0000, v106
	v_mul_f32_e32 v1, v1, v11
	v_mul_f32_e32 v8, v8, v10
	v_cvt_pk_bf16_f32 v1, v1, v8
	global_store_dword v9, v1, s[44:45] offset:64
	v_mul_f32_e32 v1, v32, v4
	v_mul_f32_e32 v8, v33, v5
	v_cndmask_b32_e32 v10, v1, v8, vcc
	ds_bpermute_b32 v10, v212, v10
	s_waitcnt lgkmcnt(0)
	v_cndmask_b32_e32 v1, v10, v1, vcc
	v_cndmask_b32_e32 v8, v8, v10, vcc
	s_waitcnt vmcnt(31)
	v_lshlrev_b32_e32 v11, 16, v107
	v_and_b32_e32 v10, 0xffff0000, v107
	v_mul_f32_e32 v1, v1, v11
	v_mul_f32_e32 v8, v8, v10
	v_cvt_pk_bf16_f32 v1, v1, v8
	global_store_dword v9, v1, s[44:45] offset:128
	v_mul_f32_e32 v1, v16, v4
	v_mul_f32_e32 v4, v17, v5
	v_cndmask_b32_e32 v5, v1, v4, vcc
	ds_bpermute_b32 v5, v212, v5
	s_waitcnt lgkmcnt(0)
	v_cndmask_b32_e32 v1, v5, v1, vcc
	v_cndmask_b32_e32 v4, v4, v5, vcc
	s_waitcnt vmcnt(31)
	v_lshlrev_b32_e32 v8, 16, v108
	v_and_b32_e32 v5, 0xffff0000, v108
	v_mul_f32_e32 v1, v1, v8
	v_mul_f32_e32 v4, v4, v5
	v_cvt_pk_bf16_f32 v1, v1, v4
	global_store_dword v9, v1, s[44:45] offset:192
	v_rcp_f32_e32 v1, v6
	v_rcp_f32_e32 v4, v7
	v_mul_f32_e32 v5, v66, v1
	v_mul_f32_e32 v6, v67, v4
	v_cndmask_b32_e32 v7, v5, v6, vcc
	ds_bpermute_b32 v7, v212, v7
	s_waitcnt lgkmcnt(0)
	v_cndmask_b32_e32 v5, v7, v5, vcc
	v_cndmask_b32_e32 v6, v6, v7, vcc
	s_waitcnt vmcnt(31)
	v_lshlrev_b32_e32 v8, 16, v109
	v_and_b32_e32 v7, 0xffff0000, v109
	v_mul_f32_e32 v5, v5, v8
	v_mul_f32_e32 v6, v6, v7
	v_cvt_pk_bf16_f32 v5, v5, v6
	global_store_dword v2, v5, s[44:45]
	v_mul_f32_e32 v5, v50, v1
	v_mul_f32_e32 v6, v51, v4
	v_cndmask_b32_e32 v7, v5, v6, vcc
	ds_bpermute_b32 v7, v212, v7
	s_waitcnt lgkmcnt(0)
	v_cndmask_b32_e32 v5, v7, v5, vcc
	v_cndmask_b32_e32 v6, v6, v7, vcc
	s_waitcnt vmcnt(31)
	v_lshlrev_b32_e32 v8, 16, v110
	v_and_b32_e32 v7, 0xffff0000, v110
	v_mul_f32_e32 v5, v5, v8
	v_mul_f32_e32 v6, v6, v7
	v_cvt_pk_bf16_f32 v5, v5, v6
	global_store_dword v2, v5, s[44:45] offset:64
	v_mul_f32_e32 v5, v34, v1
	v_mul_f32_e32 v6, v35, v4
	v_cndmask_b32_e32 v7, v5, v6, vcc
	ds_bpermute_b32 v7, v212, v7
	v_mul_f32_e32 v1, v18, v1
	v_mul_f32_e32 v4, v19, v4
	s_waitcnt lgkmcnt(0)
	v_cndmask_b32_e32 v5, v7, v5, vcc
	v_cndmask_b32_e32 v6, v6, v7, vcc
	s_waitcnt vmcnt(31)
	v_lshlrev_b32_e32 v8, 16, v111
	v_and_b32_e32 v7, 0xffff0000, v111
	v_mul_f32_e32 v5, v5, v8
	v_mul_f32_e32 v6, v6, v7
	v_cvt_pk_bf16_f32 v5, v5, v6
	global_store_dword v2, v5, s[44:45] offset:128
	v_cndmask_b32_e32 v5, v1, v4, vcc
	ds_bpermute_b32 v5, v212, v5
	s_waitcnt lgkmcnt(0)
	v_cndmask_b32_e32 v1, v5, v1, vcc
	v_cndmask_b32_e32 v4, v4, v5, vcc
	s_waitcnt vmcnt(31)
	v_lshlrev_b32_e32 v6, 16, v112
	v_and_b32_e32 v5, 0xffff0000, v112
	v_mul_f32_e32 v1, v1, v6
	v_mul_f32_e32 v4, v4, v5
	v_cvt_pk_bf16_f32 v1, v1, v4
	global_store_dword v2, v1, s[44:45] offset:192

.LBB0_1045:
	s_and_saveexec_b64 s[48:49], s[44:45]
	ds_write_b32 v180, v81
	s_or_b64 exec, exec, s[48:49]
	s_waitcnt lgkmcnt(0)
	v_lshl_add_u32 v68, v164, 4, s11
	ds_read_b128 v[70:73], v68
	v_and_b32_e32 v1, 1, v165
	v_cmp_eq_u32_e32 vcc, 0, v1
	v_and_b32_e32 v2, 30, v165
	v_lshlrev_b32_e32 v1, 10, v1
	s_waitcnt lgkmcnt(0)
	v_rcp_f32_e32 v69, v70
	v_rcp_f32_e32 v70, v71
	v_lshlrev_b32_e32 v71, 12, v164
	s_ashr_i32 s47, s46, 31
	v_or3_b32 v1, v71, v1, v2
	v_mul_f32_e32 v2, v52, v69
	v_mul_f32_e32 v52, v53, v70
	s_lshl_b64 s[16:17], s[46:47], 11
	v_readlane_b32 s13, v253, 53
	v_cndmask_b32_e32 v53, v2, v52, vcc
	s_add_u32 s13, s13, s16
	v_readlane_b32 s18, v253, 54
	ds_bpermute_b32 v53, v212, v53
	s_addc_u32 s18, s18, s17
	s_lshl_b32 s1, s1, 1
	s_add_u32 s13, s13, s1
	s_addc_u32 s18, s18, 0
	s_lshl_b32 s9, s9, 1
	s_add_u32 s46, s13, s9
	s_addc_u32 s47, s18, 0
	s_waitcnt lgkmcnt(0)
	v_cndmask_b32_e32 v71, v53, v2, vcc
	v_lshlrev_b32_e32 v2, 1, v1
	v_or_b32_e32 v74, 0x1000, v2
	v_or_b32_e32 v75, 0x4000, v2
	v_or_b32_e32 v76, 0x5000, v2
	v_or_b32_e32 v77, 0x8000, v2
	v_or_b32_e32 v78, 0x9000, v2
	v_or_b32_e32 v79, 0xc000, v2
	v_or_b32_e32 v80, 0xd000, v2
	global_load_dword v81, v2, s[46:47]
	global_load_dword v82, v2, s[46:47] offset:64
	global_load_dword v83, v2, s[46:47] offset:128
	global_load_dword v84, v2, s[46:47] offset:192
	global_load_dword v85, v74, s[46:47]
	global_load_dword v86, v74, s[46:47] offset:64
	global_load_dword v87, v74, s[46:47] offset:128
	global_load_dword v88, v74, s[46:47] offset:192
	global_load_dword v89, v75, s[46:47]
	global_load_dword v90, v75, s[46:47] offset:64
	global_load_dword v91, v75, s[46:47] offset:128
	global_load_dword v92, v75, s[46:47] offset:192
	global_load_dword v93, v76, s[46:47]
	global_load_dword v94, v76, s[46:47] offset:64
	global_load_dword v95, v76, s[46:47] offset:128
	global_load_dword v96, v76, s[46:47] offset:192
	global_load_dword v97, v77, s[46:47]
	global_load_dword v98, v77, s[46:47] offset:64
	global_load_dword v99, v77, s[46:47] offset:128
	global_load_dword v100, v77, s[46:47] offset:192
	global_load_dword v101, v78, s[46:47]
	global_load_dword v102, v78, s[46:47] offset:64
	global_load_dword v103, v78, s[46:47] offset:128
	global_load_dword v104, v78, s[46:47] offset:192
	global_load_dword v105, v79, s[46:47]
	global_load_dword v106, v79, s[46:47] offset:64
	global_load_dword v107, v79, s[46:47] offset:128
	global_load_dword v108, v79, s[46:47] offset:192
	global_load_dword v109, v80, s[46:47]
	global_load_dword v110, v80, s[46:47] offset:64
	global_load_dword v111, v80, s[46:47] offset:128
	global_load_dword v112, v80, s[46:47] offset:192
	s_nop 0
	s_nop 0
	v_readlane_b32 s13, v253, 51
	s_add_u32 s13, s13, s16
	v_readlane_b32 s16, v253, 52
	s_addc_u32 s16, s16, s17
	s_add_u32 s1, s13, s1
	s_addc_u32 s13, s16, 0
	v_cndmask_b32_e32 v52, v52, v53, vcc
	s_add_u32 s44, s1, s9
	s_addc_u32 s45, s13, 0
	s_waitcnt vmcnt(31)
	v_lshlrev_b32_e32 v53, 16, v81
	v_and_b32_e32 v1, 0xffff0000, v81
	v_mul_f32_e32 v53, v71, v53
	v_mul_f32_e32 v1, v52, v1
	v_cvt_pk_bf16_f32 v1, v53, v1
	global_store_dword v2, v1, s[44:45]
	v_mul_f32_e32 v1, v36, v69
	v_mul_f32_e32 v36, v37, v70
	v_cndmask_b32_e32 v37, v1, v36, vcc
	ds_bpermute_b32 v37, v212, v37
	s_waitcnt lgkmcnt(0)
	v_cndmask_b32_e32 v1, v37, v1, vcc
	v_cndmask_b32_e32 v36, v36, v37, vcc
	s_waitcnt vmcnt(31)
	v_lshlrev_b32_e32 v52, 16, v82
	v_and_b32_e32 v37, 0xffff0000, v82
	v_mul_f32_e32 v1, v1, v52
	v_mul_f32_e32 v36, v36, v37
	v_cvt_pk_bf16_f32 v1, v1, v36
	global_store_dword v2, v1, s[44:45] offset:64
	v_mul_f32_e32 v1, v20, v69
	v_mul_f32_e32 v20, v21, v70
	v_cndmask_b32_e32 v21, v1, v20, vcc
	ds_bpermute_b32 v21, v212, v21
	s_waitcnt lgkmcnt(0)
	v_cndmask_b32_e32 v1, v21, v1, vcc
	v_cndmask_b32_e32 v20, v20, v21, vcc
	s_waitcnt vmcnt(31)
	v_lshlrev_b32_e32 v36, 16, v83
	v_and_b32_e32 v21, 0xffff0000, v83
	v_mul_f32_e32 v1, v1, v36
	v_mul_f32_e32 v20, v20, v21
	v_cvt_pk_bf16_f32 v1, v1, v20
	global_store_dword v2, v1, s[44:45] offset:128
	v_mul_f32_e32 v1, v4, v69
	v_mul_f32_e32 v4, v5, v70
	v_cndmask_b32_e32 v5, v1, v4, vcc
	ds_bpermute_b32 v5, v212, v5
	s_waitcnt lgkmcnt(0)
	v_cndmask_b32_e32 v1, v5, v1, vcc
	v_cndmask_b32_e32 v4, v4, v5, vcc
	s_waitcnt vmcnt(31)
	v_lshlrev_b32_e32 v20, 16, v84
	v_and_b32_e32 v5, 0xffff0000, v84
	v_mul_f32_e32 v1, v1, v20
	v_mul_f32_e32 v4, v4, v5
	v_cvt_pk_bf16_f32 v1, v1, v4
	global_store_dword v2, v1, s[44:45] offset:192
	v_rcp_f32_e32 v1, v72
	v_rcp_f32_e32 v4, v73
	v_mul_f32_e32 v5, v54, v1
	v_mul_f32_e32 v20, v55, v4
	v_cndmask_b32_e32 v21, v5, v20, vcc
	ds_bpermute_b32 v21, v212, v21
	s_waitcnt lgkmcnt(0)
	v_cndmask_b32_e32 v5, v21, v5, vcc
	v_cndmask_b32_e32 v20, v20, v21, vcc
	v_or_b32_e32 v21, 0x1000, v2
	s_waitcnt vmcnt(31)
	v_lshlrev_b32_e32 v37, 16, v85
	v_and_b32_e32 v36, 0xffff0000, v85
	v_mul_f32_e32 v5, v5, v37
	v_mul_f32_e32 v20, v20, v36
	v_cvt_pk_bf16_f32 v5, v5, v20
	global_store_dword v21, v5, s[44:45]
	v_mul_f32_e32 v5, v38, v1
	v_mul_f32_e32 v20, v39, v4
	v_cndmask_b32_e32 v36, v5, v20, vcc
	ds_bpermute_b32 v36, v212, v36
	s_waitcnt lgkmcnt(0)
	v_cndmask_b32_e32 v5, v36, v5, vcc
	v_cndmask_b32_e32 v20, v20, v36, vcc
	s_waitcnt vmcnt(31)
	v_lshlrev_b32_e32 v37, 16, v86
	v_and_b32_e32 v36, 0xffff0000, v86
	v_mul_f32_e32 v5, v5, v37
	v_mul_f32_e32 v20, v20, v36
	v_cvt_pk_bf16_f32 v5, v5, v20
	global_store_dword v21, v5, s[44:45] offset:64
	v_mul_f32_e32 v5, v22, v1
	v_mul_f32_e32 v20, v23, v4
	v_cndmask_b32_e32 v22, v5, v20, vcc
	ds_bpermute_b32 v22, v212, v22
	v_mul_f32_e32 v1, v6, v1
	v_mul_f32_e32 v4, v7, v4
	s_waitcnt lgkmcnt(0)
	v_cndmask_b32_e32 v5, v22, v5, vcc
	v_cndmask_b32_e32 v20, v20, v22, vcc
	s_waitcnt vmcnt(31)
	v_lshlrev_b32_e32 v23, 16, v87
	v_and_b32_e32 v22, 0xffff0000, v87
	v_mul_f32_e32 v5, v5, v23
	v_mul_f32_e32 v20, v20, v22
	v_cvt_pk_bf16_f32 v5, v5, v20
	global_store_dword v21, v5, s[44:45] offset:128
	v_cndmask_b32_e32 v5, v1, v4, vcc
	ds_bpermute_b32 v5, v212, v5
	s_waitcnt lgkmcnt(0)
	v_cndmask_b32_e32 v1, v5, v1, vcc
	v_cndmask_b32_e32 v4, v4, v5, vcc
	s_waitcnt vmcnt(31)
	v_lshlrev_b32_e32 v6, 16, v88
	v_and_b32_e32 v5, 0xffff0000, v88
	v_mul_f32_e32 v1, v1, v6
	v_mul_f32_e32 v4, v4, v5
	v_cvt_pk_bf16_f32 v1, v1, v4
	ds_read_b128 v[4:7], v68 offset:32
	global_store_dword v21, v1, s[44:45] offset:192
	s_waitcnt lgkmcnt(0)
	v_rcp_f32_e32 v4, v4
	v_rcp_f32_e32 v5, v5
	v_mul_f32_e32 v1, v56, v4
	v_mul_f32_e32 v20, v57, v5
	v_cndmask_b32_e32 v21, v1, v20, vcc
	ds_bpermute_b32 v21, v212, v21
	s_waitcnt lgkmcnt(0)
	v_cndmask_b32_e32 v1, v21, v1, vcc
	v_cndmask_b32_e32 v20, v20, v21, vcc
	v_or_b32_e32 v21, 0x4000, v2
	s_waitcnt vmcnt(31)
	v_lshlrev_b32_e32 v23, 16, v89
	v_and_b32_e32 v22, 0xffff0000, v89
	v_mul_f32_e32 v1, v1, v23
	v_mul_f32_e32 v20, v20, v22
	v_cvt_pk_bf16_f32 v1, v1, v20
	global_store_dword v21, v1, s[44:45]
	v_mul_f32_e32 v1, v40, v4
	v_mul_f32_e32 v20, v41, v5
	v_cndmask_b32_e32 v22, v1, v20, vcc
	ds_bpermute_b32 v22, v212, v22
	s_waitcnt lgkmcnt(0)
	v_cndmask_b32_e32 v1, v22, v1, vcc
	v_cndmask_b32_e32 v20, v20, v22, vcc
	s_waitcnt vmcnt(31)
	v_lshlrev_b32_e32 v23, 16, v90
	v_and_b32_e32 v22, 0xffff0000, v90
	v_mul_f32_e32 v1, v1, v23
	v_mul_f32_e32 v20, v20, v22
	v_cvt_pk_bf16_f32 v1, v1, v20
	global_store_dword v21, v1, s[44:45] offset:64
	v_mul_f32_e32 v1, v24, v4
	v_mul_f32_e32 v20, v25, v5
	v_cndmask_b32_e32 v22, v1, v20, vcc
	ds_bpermute_b32 v22, v212, v22
	s_waitcnt lgkmcnt(0)
	v_cndmask_b32_e32 v1, v22, v1, vcc
	v_cndmask_b32_e32 v20, v20, v22, vcc
	s_waitcnt vmcnt(31)
	v_lshlrev_b32_e32 v23, 16, v91
	v_and_b32_e32 v22, 0xffff0000, v91
	v_mul_f32_e32 v1, v1, v23
	v_mul_f32_e32 v20, v20, v22
	v_cvt_pk_bf16_f32 v1, v1, v20
	global_store_dword v21, v1, s[44:45] offset:128
	v_mul_f32_e32 v1, v8, v4
	v_mul_f32_e32 v4, v9, v5
	v_cndmask_b32_e32 v5, v1, v4, vcc
	ds_bpermute_b32 v5, v212, v5
	s_waitcnt lgkmcnt(0)
	v_cndmask_b32_e32 v1, v5, v1, vcc
	v_cndmask_b32_e32 v4, v4, v5, vcc
	s_waitcnt vmcnt(31)
	v_lshlrev_b32_e32 v8, 16, v92
	v_and_b32_e32 v5, 0xffff0000, v92
	v_mul_f32_e32 v1, v1, v8
	v_mul_f32_e32 v4, v4, v5
	v_cvt_pk_bf16_f32 v1, v1, v4
	global_store_dword v21, v1, s[44:45] offset:192
	v_rcp_f32_e32 v1, v6
	v_rcp_f32_e32 v4, v7
	v_mul_f32_e32 v5, v58, v1
	v_mul_f32_e32 v6, v59, v4
	v_cndmask_b32_e32 v7, v5, v6, vcc
	ds_bpermute_b32 v7, v212, v7
	s_waitcnt lgkmcnt(0)
	v_cndmask_b32_e32 v5, v7, v5, vcc
	v_cndmask_b32_e32 v6, v6, v7, vcc
	v_or_b32_e32 v7, 0x5000, v2
	s_waitcnt vmcnt(31)
	v_lshlrev_b32_e32 v9, 16, v93
	v_and_b32_e32 v8, 0xffff0000, v93
	v_mul_f32_e32 v5, v5, v9
	v_mul_f32_e32 v6, v6, v8
	v_cvt_pk_bf16_f32 v5, v5, v6
	global_store_dword v7, v5, s[44:45]
	v_mul_f32_e32 v5, v42, v1
	v_mul_f32_e32 v6, v43, v4
	v_cndmask_b32_e32 v8, v5, v6, vcc
	ds_bpermute_b32 v8, v212, v8
	s_waitcnt lgkmcnt(0)
	v_cndmask_b32_e32 v5, v8, v5, vcc
	v_cndmask_b32_e32 v6, v6, v8, vcc
	s_waitcnt vmcnt(31)
	v_lshlrev_b32_e32 v9, 16, v94
	v_and_b32_e32 v8, 0xffff0000, v94
	v_mul_f32_e32 v5, v5, v9
	v_mul_f32_e32 v6, v6, v8
	v_cvt_pk_bf16_f32 v5, v5, v6
	global_store_dword v7, v5, s[44:45] offset:64
	v_mul_f32_e32 v5, v26, v1
	v_mul_f32_e32 v6, v27, v4
	v_cndmask_b32_e32 v8, v5, v6, vcc
	ds_bpermute_b32 v8, v212, v8
	v_mul_f32_e32 v1, v10, v1
	v_mul_f32_e32 v4, v11, v4
	s_waitcnt lgkmcnt(0)
	v_cndmask_b32_e32 v5, v8, v5, vcc
	v_cndmask_b32_e32 v6, v6, v8, vcc
	s_waitcnt vmcnt(31)
	v_lshlrev_b32_e32 v9, 16, v95
	v_and_b32_e32 v8, 0xffff0000, v95
	v_mul_f32_e32 v5, v5, v9
	v_mul_f32_e32 v6, v6, v8
	v_cvt_pk_bf16_f32 v5, v5, v6
	global_store_dword v7, v5, s[44:45] offset:128
	v_cndmask_b32_e32 v5, v1, v4, vcc
	ds_bpermute_b32 v5, v212, v5
	s_waitcnt lgkmcnt(0)
	v_cndmask_b32_e32 v1, v5, v1, vcc
	v_cndmask_b32_e32 v4, v4, v5, vcc
	s_waitcnt vmcnt(31)
	v_lshlrev_b32_e32 v6, 16, v96
	v_and_b32_e32 v5, 0xffff0000, v96
	v_mul_f32_e32 v1, v1, v6
	v_mul_f32_e32 v4, v4, v5
	v_cvt_pk_bf16_f32 v1, v1, v4
	global_store_dword v7, v1, s[44:45] offset:192
	ds_read_b128 v[4:7], v68 offset:64
	s_waitcnt lgkmcnt(0)
	v_rcp_f32_e32 v1, v4
	v_rcp_f32_e32 v4, v5
	v_mul_f32_e32 v5, v60, v1
	v_mul_f32_e32 v8, v61, v4
	v_cndmask_b32_e32 v9, v5, v8, vcc
	ds_bpermute_b32 v9, v212, v9
	s_waitcnt lgkmcnt(0)
	v_cndmask_b32_e32 v5, v9, v5, vcc
	v_cndmask_b32_e32 v8, v8, v9, vcc
	v_or_b32_e32 v9, 0x8000, v2
	s_waitcnt vmcnt(31)
	v_lshlrev_b32_e32 v11, 16, v97
	v_and_b32_e32 v10, 0xffff0000, v97
	v_mul_f32_e32 v5, v5, v11
	v_mul_f32_e32 v8, v8, v10
	v_cvt_pk_bf16_f32 v5, v5, v8
	global_store_dword v9, v5, s[44:45]
	v_mul_f32_e32 v5, v44, v1
	v_mul_f32_e32 v8, v45, v4
	v_cndmask_b32_e32 v10, v5, v8, vcc
	ds_bpermute_b32 v10, v212, v10
	s_waitcnt lgkmcnt(0)
	v_cndmask_b32_e32 v5, v10, v5, vcc
	v_cndmask_b32_e32 v8, v8, v10, vcc
	s_waitcnt vmcnt(31)
	v_lshlrev_b32_e32 v11, 16, v98
	v_and_b32_e32 v10, 0xffff0000, v98
	v_mul_f32_e32 v5, v5, v11
	v_mul_f32_e32 v8, v8, v10
	v_cvt_pk_bf16_f32 v5, v5, v8
	global_store_dword v9, v5, s[44:45] offset:64
	v_mul_f32_e32 v5, v28, v1
	v_mul_f32_e32 v8, v29, v4
	v_cndmask_b32_e32 v10, v5, v8, vcc
	ds_bpermute_b32 v10, v212, v10
	v_mul_f32_e32 v1, v12, v1
	v_mul_f32_e32 v4, v13, v4
	s_waitcnt lgkmcnt(0)
	v_cndmask_b32_e32 v5, v10, v5, vcc
	v_cndmask_b32_e32 v8, v8, v10, vcc
	s_waitcnt vmcnt(31)
	v_lshlrev_b32_e32 v11, 16, v99
	v_and_b32_e32 v10, 0xffff0000, v99
	v_mul_f32_e32 v5, v5, v11
	v_mul_f32_e32 v8, v8, v10
	v_cvt_pk_bf16_f32 v5, v5, v8
	global_store_dword v9, v5, s[44:45] offset:128
	v_cndmask_b32_e32 v5, v1, v4, vcc
	ds_bpermute_b32 v5, v212, v5
	s_waitcnt lgkmcnt(0)
	v_cndmask_b32_e32 v1, v5, v1, vcc
	v_cndmask_b32_e32 v4, v4, v5, vcc
	s_waitcnt vmcnt(31)
	v_lshlrev_b32_e32 v8, 16, v100
	v_and_b32_e32 v5, 0xffff0000, v100
	v_mul_f32_e32 v1, v1, v8
	v_mul_f32_e32 v4, v4, v5
	v_cvt_pk_bf16_f32 v1, v1, v4
	global_store_dword v9, v1, s[44:45] offset:192
	v_rcp_f32_e32 v1, v6
	v_rcp_f32_e32 v4, v7
	v_mul_f32_e32 v5, v62, v1
	v_mul_f32_e32 v6, v63, v4
	v_cndmask_b32_e32 v7, v5, v6, vcc
	ds_bpermute_b32 v7, v212, v7
	s_waitcnt lgkmcnt(0)
	v_cndmask_b32_e32 v5, v7, v5, vcc
	v_cndmask_b32_e32 v6, v6, v7, vcc
	v_or_b32_e32 v7, 0x9000, v2
	s_waitcnt vmcnt(31)
	v_lshlrev_b32_e32 v9, 16, v101
	v_and_b32_e32 v8, 0xffff0000, v101
	v_mul_f32_e32 v5, v5, v9
	v_mul_f32_e32 v6, v6, v8
	v_cvt_pk_bf16_f32 v5, v5, v6
	global_store_dword v7, v5, s[44:45]
	v_mul_f32_e32 v5, v46, v1
	v_mul_f32_e32 v6, v47, v4
	v_cndmask_b32_e32 v8, v5, v6, vcc
	ds_bpermute_b32 v8, v212, v8
	s_waitcnt lgkmcnt(0)
	v_cndmask_b32_e32 v5, v8, v5, vcc
	v_cndmask_b32_e32 v6, v6, v8, vcc
	s_waitcnt vmcnt(31)
	v_lshlrev_b32_e32 v9, 16, v102
	v_and_b32_e32 v8, 0xffff0000, v102
	v_mul_f32_e32 v5, v5, v9
	v_mul_f32_e32 v6, v6, v8
	v_cvt_pk_bf16_f32 v5, v5, v6
	global_store_dword v7, v5, s[44:45] offset:64
	v_mul_f32_e32 v5, v30, v1
	v_mul_f32_e32 v6, v31, v4
	v_cndmask_b32_e32 v8, v5, v6, vcc
	ds_bpermute_b32 v8, v212, v8
	v_mul_f32_e32 v1, v14, v1
	v_mul_f32_e32 v4, v15, v4
	s_waitcnt lgkmcnt(0)
	v_cndmask_b32_e32 v5, v8, v5, vcc
	v_cndmask_b32_e32 v6, v6, v8, vcc
	s_waitcnt vmcnt(31)
	v_lshlrev_b32_e32 v9, 16, v103
	v_and_b32_e32 v8, 0xffff0000, v103
	v_mul_f32_e32 v5, v5, v9
	v_mul_f32_e32 v6, v6, v8
	v_cvt_pk_bf16_f32 v5, v5, v6
	global_store_dword v7, v5, s[44:45] offset:128
	v_cndmask_b32_e32 v5, v1, v4, vcc
	ds_bpermute_b32 v5, v212, v5
	s_waitcnt lgkmcnt(0)
	v_cndmask_b32_e32 v1, v5, v1, vcc
	v_cndmask_b32_e32 v4, v4, v5, vcc
	s_waitcnt vmcnt(31)
	v_lshlrev_b32_e32 v6, 16, v104
	v_and_b32_e32 v5, 0xffff0000, v104
	v_mul_f32_e32 v1, v1, v6
	v_mul_f32_e32 v4, v4, v5
	v_cvt_pk_bf16_f32 v1, v1, v4
	global_store_dword v7, v1, s[44:45] offset:192
	ds_read_b128 v[4:7], v68 offset:96
	s_waitcnt lgkmcnt(0)
	v_rcp_f32_e32 v4, v4
	v_rcp_f32_e32 v5, v5
	v_mul_f32_e32 v1, v64, v4
	v_mul_f32_e32 v8, v65, v5
	v_cndmask_b32_e32 v9, v1, v8, vcc
	ds_bpermute_b32 v9, v212, v9
	s_waitcnt lgkmcnt(0)
	v_cndmask_b32_e32 v1, v9, v1, vcc
	v_cndmask_b32_e32 v8, v8, v9, vcc
	v_or_b32_e32 v9, 0xc000, v2
	v_or_b32_e32 v2, 0xd000, v2
	s_waitcnt vmcnt(31)
	v_lshlrev_b32_e32 v11, 16, v105
	v_and_b32_e32 v10, 0xffff0000, v105
	v_mul_f32_e32 v1, v1, v11
	v_mul_f32_e32 v8, v8, v10
	v_cvt_pk_bf16_f32 v1, v1, v8
	global_store_dword v9, v1, s[44:45]
	v_mul_f32_e32 v1, v48, v4
	v_mul_f32_e32 v8, v49, v5
	v_cndmask_b32_e32 v10, v1, v8, vcc
	ds_bpermute_b32 v10, v212, v10
	s_waitcnt lgkmcnt(0)
	v_cndmask_b32_e32 v1, v10, v1, vcc
	v_cndmask_b32_e32 v8, v8, v10, vcc
	s_waitcnt vmcnt(31)
	v_lshlrev_b32_e32 v11, 16, v106
	v_and_b32_e32 v10, 0xffff0000, v106
	v_mul_f32_e32 v1, v1, v11
	v_mul_f32_e32 v8, v8, v10
	v_cvt_pk_bf16_f32 v1, v1, v8
	global_store_dword v9, v1, s[44:45] offset:64
	v_mul_f32_e32 v1, v32, v4
	v_mul_f32_e32 v8, v33, v5
	v_cndmask_b32_e32 v10, v1, v8, vcc
	ds_bpermute_b32 v10, v212, v10
	s_waitcnt lgkmcnt(0)
	v_cndmask_b32_e32 v1, v10, v1, vcc
	v_cndmask_b32_e32 v8, v8, v10, vcc
	s_waitcnt vmcnt(31)
	v_lshlrev_b32_e32 v11, 16, v107
	v_and_b32_e32 v10, 0xffff0000, v107
	v_mul_f32_e32 v1, v1, v11
	v_mul_f32_e32 v8, v8, v10
	v_cvt_pk_bf16_f32 v1, v1, v8
	global_store_dword v9, v1, s[44:45] offset:128
	v_mul_f32_e32 v1, v16, v4
	v_mul_f32_e32 v4, v17, v5
	v_cndmask_b32_e32 v5, v1, v4, vcc
	ds_bpermute_b32 v5, v212, v5
	s_waitcnt lgkmcnt(0)
	v_cndmask_b32_e32 v1, v5, v1, vcc
	v_cndmask_b32_e32 v4, v4, v5, vcc
	s_waitcnt vmcnt(31)
	v_lshlrev_b32_e32 v8, 16, v108
	v_and_b32_e32 v5, 0xffff0000, v108
	v_mul_f32_e32 v1, v1, v8
	v_mul_f32_e32 v4, v4, v5
	v_cvt_pk_bf16_f32 v1, v1, v4
	global_store_dword v9, v1, s[44:45] offset:192
	v_rcp_f32_e32 v1, v6
	v_rcp_f32_e32 v4, v7
	v_mul_f32_e32 v5, v66, v1
	v_mul_f32_e32 v6, v67, v4
	v_cndmask_b32_e32 v7, v5, v6, vcc
	ds_bpermute_b32 v7, v212, v7
	s_waitcnt lgkmcnt(0)
	v_cndmask_b32_e32 v5, v7, v5, vcc
	v_cndmask_b32_e32 v6, v6, v7, vcc
	s_waitcnt vmcnt(31)
	v_lshlrev_b32_e32 v8, 16, v109
	v_and_b32_e32 v7, 0xffff0000, v109
	v_mul_f32_e32 v5, v5, v8
	v_mul_f32_e32 v6, v6, v7
	v_cvt_pk_bf16_f32 v5, v5, v6
	global_store_dword v2, v5, s[44:45]
	v_mul_f32_e32 v5, v50, v1
	v_mul_f32_e32 v6, v51, v4
	v_cndmask_b32_e32 v7, v5, v6, vcc
	ds_bpermute_b32 v7, v212, v7
	s_waitcnt lgkmcnt(0)
	v_cndmask_b32_e32 v5, v7, v5, vcc
	v_cndmask_b32_e32 v6, v6, v7, vcc
	s_waitcnt vmcnt(31)
	v_lshlrev_b32_e32 v8, 16, v110
	v_and_b32_e32 v7, 0xffff0000, v110
	v_mul_f32_e32 v5, v5, v8
	v_mul_f32_e32 v6, v6, v7
	v_cvt_pk_bf16_f32 v5, v5, v6
	global_store_dword v2, v5, s[44:45] offset:64
	v_mul_f32_e32 v5, v34, v1
	v_mul_f32_e32 v6, v35, v4
	v_cndmask_b32_e32 v7, v5, v6, vcc
	ds_bpermute_b32 v7, v212, v7
	v_mul_f32_e32 v1, v18, v1
	v_mul_f32_e32 v4, v19, v4
	s_waitcnt lgkmcnt(0)
	v_cndmask_b32_e32 v5, v7, v5, vcc
	v_cndmask_b32_e32 v6, v6, v7, vcc
	s_waitcnt vmcnt(31)
	v_lshlrev_b32_e32 v8, 16, v111
	v_and_b32_e32 v7, 0xffff0000, v111
	v_mul_f32_e32 v5, v5, v8
	v_mul_f32_e32 v6, v6, v7
	v_cvt_pk_bf16_f32 v5, v5, v6
	global_store_dword v2, v5, s[44:45] offset:128
	v_cndmask_b32_e32 v5, v1, v4, vcc
	ds_bpermute_b32 v5, v212, v5
	s_waitcnt lgkmcnt(0)
	v_cndmask_b32_e32 v1, v5, v1, vcc
	v_cndmask_b32_e32 v4, v4, v5, vcc
	s_waitcnt vmcnt(31)
	v_lshlrev_b32_e32 v6, 16, v112
	v_and_b32_e32 v5, 0xffff0000, v112
	v_mul_f32_e32 v1, v1, v6
	v_mul_f32_e32 v4, v4, v5
	v_cvt_pk_bf16_f32 v1, v1, v4
	global_store_dword v2, v1, s[44:45] offset:192

.LBB0_1071:
	s_or_b64 exec, exec, s[44:45]
	s_ashr_i32 s47, s46, 31
	s_lshl_b64 s[18:19], s[46:47], 12
	v_readlane_b32 s1, v254, 29
	s_add_u32 s1, s1, s18
	v_readlane_b32 s9, v254, 30
	s_addc_u32 s9, s9, s19
	s_lshl_b32 s13, s16, 8
	s_add_u32 s46, s1, s13
	s_addc_u32 s47, s9, 0
	v_readlane_b32 s1, v254, 31
	s_add_u32 s1, s1, s18
	v_readlane_b32 s9, v254, 32
	s_addc_u32 s9, s9, s19
	s_add_u32 s44, s1, s13
	v_readlane_b32 s1, v254, 28
	s_waitcnt lgkmcnt(0)
	v_and_b32_e32 v1, 1, v164
	v_cmp_eq_u32_e32 vcc, 0, v1
	v_lshl_add_u32 v8, v172, 4, s1
	ds_read_b128 v[4:7], v8
	v_and_b32_e32 v2, 30, v164
	v_lshlrev_b32_e32 v9, 13, v172
	v_lshlrev_b32_e32 v1, 11, v1
	v_or3_b32 v1, v9, v1, v2
	s_waitcnt lgkmcnt(0)
	v_rcp_f32_e32 v4, v4
	v_rcp_f32_e32 v5, v5
	s_addc_u32 s45, s9, 0
	v_mul_f32_e32 v2, v66, v4
	v_mul_f32_e32 v9, v67, v5
	v_cndmask_b32_e32 v10, v2, v9, vcc
	ds_bpermute_b32 v10, v212, v10
	s_waitcnt lgkmcnt(0)
	v_cndmask_b32_e32 v11, v10, v2, vcc
	v_lshlrev_b32_e32 v2, 1, v1
	v_or_b32_e32 v13, 0x2000, v2
	v_or_b32_e32 v14, 0x8000, v2
	v_or_b32_e32 v15, 0xa000, v2
	v_or_b32_e32 v16, 0x10000, v2
	v_or_b32_e32 v17, 0x12000, v2
	v_or_b32_e32 v66, 0x18000, v2
	v_or_b32_e32 v82, 0x1a000, v2
	global_load_dword v83, v2, s[46:47]
	global_load_dword v84, v2, s[46:47] offset:64
	global_load_dword v85, v2, s[46:47] offset:128
	global_load_dword v86, v2, s[46:47] offset:192
	global_load_dword v87, v13, s[46:47]
	global_load_dword v88, v13, s[46:47] offset:64
	global_load_dword v89, v13, s[46:47] offset:128
	global_load_dword v90, v13, s[46:47] offset:192
	global_load_dword v91, v14, s[46:47]
	global_load_dword v92, v14, s[46:47] offset:64
	global_load_dword v93, v14, s[46:47] offset:128
	global_load_dword v94, v14, s[46:47] offset:192
	global_load_dword v95, v15, s[46:47]
	global_load_dword v96, v15, s[46:47] offset:64
	global_load_dword v97, v15, s[46:47] offset:128
	global_load_dword v98, v15, s[46:47] offset:192
	global_load_dword v99, v16, s[46:47]
	global_load_dword v100, v16, s[46:47] offset:64
	global_load_dword v101, v16, s[46:47] offset:128
	global_load_dword v102, v16, s[46:47] offset:192
	global_load_dword v103, v17, s[46:47]
	global_load_dword v104, v17, s[46:47] offset:64
	global_load_dword v105, v17, s[46:47] offset:128
	global_load_dword v106, v17, s[46:47] offset:192
	global_load_dword v107, v66, s[46:47]
	global_load_dword v108, v66, s[46:47] offset:64
	global_load_dword v109, v66, s[46:47] offset:128
	global_load_dword v110, v66, s[46:47] offset:192
	global_load_dword v111, v82, s[46:47]
	global_load_dword v112, v82, s[46:47] offset:64
	global_load_dword v113, v82, s[46:47] offset:128
	global_load_dword v114, v82, s[46:47] offset:192
	s_nop 0
	s_nop 0
	v_cndmask_b32_e32 v9, v9, v10, vcc
	s_waitcnt vmcnt(31)
	v_lshlrev_b32_e32 v10, 16, v83
	v_and_b32_e32 v1, 0xffff0000, v83
	v_mul_f32_e32 v10, v11, v10
	v_mul_f32_e32 v1, v9, v1
	v_cvt_pk_bf16_f32 v1, v10, v1
	global_store_dword v2, v1, s[44:45]
	v_mul_f32_e32 v1, v50, v4
	v_mul_f32_e32 v9, v51, v5
	v_cndmask_b32_e32 v10, v1, v9, vcc
	ds_bpermute_b32 v10, v212, v10
	s_waitcnt lgkmcnt(0)
	v_cndmask_b32_e32 v1, v10, v1, vcc
	v_cndmask_b32_e32 v9, v9, v10, vcc
	s_waitcnt vmcnt(31)
	v_lshlrev_b32_e32 v11, 16, v84
	v_and_b32_e32 v10, 0xffff0000, v84
	v_mul_f32_e32 v1, v1, v11
	v_mul_f32_e32 v9, v9, v10
	v_cvt_pk_bf16_f32 v1, v1, v9
	global_store_dword v2, v1, s[44:45] offset:64
	v_mul_f32_e32 v1, v34, v4
	v_mul_f32_e32 v9, v35, v5
	v_cndmask_b32_e32 v10, v1, v9, vcc
	ds_bpermute_b32 v10, v212, v10
	s_waitcnt lgkmcnt(0)
	v_cndmask_b32_e32 v1, v10, v1, vcc
	v_cndmask_b32_e32 v9, v9, v10, vcc
	s_waitcnt vmcnt(31)
	v_lshlrev_b32_e32 v11, 16, v85
	v_and_b32_e32 v10, 0xffff0000, v85
	v_mul_f32_e32 v1, v1, v11
	v_mul_f32_e32 v9, v9, v10
	v_cvt_pk_bf16_f32 v1, v1, v9
	global_store_dword v2, v1, s[44:45] offset:128
	v_mul_f32_e32 v1, v18, v4
	v_mul_f32_e32 v4, v19, v5
	v_cndmask_b32_e32 v5, v1, v4, vcc
	ds_bpermute_b32 v5, v212, v5
	s_waitcnt lgkmcnt(0)
	v_cndmask_b32_e32 v1, v5, v1, vcc
	v_cndmask_b32_e32 v4, v4, v5, vcc
	s_waitcnt vmcnt(31)
	v_lshlrev_b32_e32 v9, 16, v86
	v_and_b32_e32 v5, 0xffff0000, v86
	v_mul_f32_e32 v1, v1, v9
	v_mul_f32_e32 v4, v4, v5
	v_cvt_pk_bf16_f32 v1, v1, v4
	global_store_dword v2, v1, s[44:45] offset:192
	v_rcp_f32_e32 v1, v6
	v_rcp_f32_e32 v4, v7
	v_mul_f32_e32 v5, v68, v1
	v_mul_f32_e32 v6, v69, v4
	v_cndmask_b32_e32 v7, v5, v6, vcc
	ds_bpermute_b32 v7, v212, v7
	s_waitcnt lgkmcnt(0)
	v_cndmask_b32_e32 v5, v7, v5, vcc
	v_cndmask_b32_e32 v6, v6, v7, vcc
	v_or_b32_e32 v7, 0x2000, v2
	s_waitcnt vmcnt(31)
	v_lshlrev_b32_e32 v10, 16, v87
	v_and_b32_e32 v9, 0xffff0000, v87
	v_mul_f32_e32 v5, v5, v10
	v_mul_f32_e32 v6, v6, v9
	v_cvt_pk_bf16_f32 v5, v5, v6
	global_store_dword v7, v5, s[44:45]
	v_mul_f32_e32 v5, v52, v1
	v_mul_f32_e32 v6, v53, v4
	v_cndmask_b32_e32 v9, v5, v6, vcc
	ds_bpermute_b32 v9, v212, v9
	s_waitcnt lgkmcnt(0)
	v_cndmask_b32_e32 v5, v9, v5, vcc
	v_cndmask_b32_e32 v6, v6, v9, vcc
	s_waitcnt vmcnt(31)
	v_lshlrev_b32_e32 v10, 16, v88
	v_and_b32_e32 v9, 0xffff0000, v88
	v_mul_f32_e32 v5, v5, v10
	v_mul_f32_e32 v6, v6, v9
	v_cvt_pk_bf16_f32 v5, v5, v6
	global_store_dword v7, v5, s[44:45] offset:64
	v_mul_f32_e32 v5, v36, v1
	v_mul_f32_e32 v6, v37, v4
	v_cndmask_b32_e32 v9, v5, v6, vcc
	ds_bpermute_b32 v9, v212, v9
	v_mul_f32_e32 v1, v20, v1
	v_mul_f32_e32 v4, v21, v4
	s_waitcnt lgkmcnt(0)
	v_cndmask_b32_e32 v5, v9, v5, vcc
	v_cndmask_b32_e32 v6, v6, v9, vcc
	s_waitcnt vmcnt(31)
	v_lshlrev_b32_e32 v10, 16, v89
	v_and_b32_e32 v9, 0xffff0000, v89
	v_mul_f32_e32 v5, v5, v10
	v_mul_f32_e32 v6, v6, v9
	v_cvt_pk_bf16_f32 v5, v5, v6
	global_store_dword v7, v5, s[44:45] offset:128
	v_cndmask_b32_e32 v5, v1, v4, vcc
	ds_bpermute_b32 v5, v212, v5
	s_waitcnt lgkmcnt(0)
	v_cndmask_b32_e32 v1, v5, v1, vcc
	v_cndmask_b32_e32 v4, v4, v5, vcc
	s_waitcnt vmcnt(31)
	v_lshlrev_b32_e32 v6, 16, v90
	v_and_b32_e32 v5, 0xffff0000, v90
	v_mul_f32_e32 v1, v1, v6
	v_mul_f32_e32 v4, v4, v5
	v_cvt_pk_bf16_f32 v1, v1, v4
	global_store_dword v7, v1, s[44:45] offset:192
	ds_read_b128 v[4:7], v8 offset:32
	s_waitcnt lgkmcnt(0)
	v_rcp_f32_e32 v4, v4
	v_rcp_f32_e32 v5, v5
	v_mul_f32_e32 v1, v70, v4
	v_mul_f32_e32 v9, v71, v5
	v_cndmask_b32_e32 v10, v1, v9, vcc
	ds_bpermute_b32 v10, v212, v10
	s_waitcnt lgkmcnt(0)
	v_cndmask_b32_e32 v1, v10, v1, vcc
	v_cndmask_b32_e32 v9, v9, v10, vcc
	v_or_b32_e32 v10, 0x8000, v2
	s_waitcnt vmcnt(31)
	v_lshlrev_b32_e32 v12, 16, v91
	v_and_b32_e32 v11, 0xffff0000, v91
	v_mul_f32_e32 v1, v1, v12
	v_mul_f32_e32 v9, v9, v11
	v_cvt_pk_bf16_f32 v1, v1, v9
	global_store_dword v10, v1, s[44:45]
	v_mul_f32_e32 v1, v54, v4
	v_mul_f32_e32 v9, v55, v5
	v_cndmask_b32_e32 v11, v1, v9, vcc
	ds_bpermute_b32 v11, v212, v11
	s_waitcnt lgkmcnt(0)
	v_cndmask_b32_e32 v1, v11, v1, vcc
	v_cndmask_b32_e32 v9, v9, v11, vcc
	s_waitcnt vmcnt(31)
	v_lshlrev_b32_e32 v12, 16, v92
	v_and_b32_e32 v11, 0xffff0000, v92
	v_mul_f32_e32 v1, v1, v12
	v_mul_f32_e32 v9, v9, v11
	v_cvt_pk_bf16_f32 v1, v1, v9
	global_store_dword v10, v1, s[44:45] offset:64
	v_mul_f32_e32 v1, v38, v4
	v_mul_f32_e32 v9, v39, v5
	v_cndmask_b32_e32 v11, v1, v9, vcc
	ds_bpermute_b32 v11, v212, v11
	s_waitcnt lgkmcnt(0)
	v_cndmask_b32_e32 v1, v11, v1, vcc
	v_cndmask_b32_e32 v9, v9, v11, vcc
	s_waitcnt vmcnt(31)
	v_lshlrev_b32_e32 v12, 16, v93
	v_and_b32_e32 v11, 0xffff0000, v93
	v_mul_f32_e32 v1, v1, v12
	v_mul_f32_e32 v9, v9, v11
	v_cvt_pk_bf16_f32 v1, v1, v9
	global_store_dword v10, v1, s[44:45] offset:128
	v_mul_f32_e32 v1, v22, v4
	v_mul_f32_e32 v4, v23, v5
	v_cndmask_b32_e32 v5, v1, v4, vcc
	ds_bpermute_b32 v5, v212, v5
	s_waitcnt lgkmcnt(0)
	v_cndmask_b32_e32 v1, v5, v1, vcc
	v_cndmask_b32_e32 v4, v4, v5, vcc
	s_waitcnt vmcnt(31)
	v_lshlrev_b32_e32 v9, 16, v94
	v_and_b32_e32 v5, 0xffff0000, v94
	v_mul_f32_e32 v1, v1, v9
	v_mul_f32_e32 v4, v4, v5
	v_cvt_pk_bf16_f32 v1, v1, v4
	global_store_dword v10, v1, s[44:45] offset:192
	v_rcp_f32_e32 v1, v6
	v_rcp_f32_e32 v4, v7
	v_mul_f32_e32 v5, v72, v1
	v_mul_f32_e32 v6, v73, v4
	v_cndmask_b32_e32 v7, v5, v6, vcc
	ds_bpermute_b32 v7, v212, v7
	s_waitcnt lgkmcnt(0)
	v_cndmask_b32_e32 v5, v7, v5, vcc
	v_cndmask_b32_e32 v6, v6, v7, vcc
	v_or_b32_e32 v7, 0xa000, v2
	s_waitcnt vmcnt(31)
	v_lshlrev_b32_e32 v10, 16, v95
	v_and_b32_e32 v9, 0xffff0000, v95
	v_mul_f32_e32 v5, v5, v10
	v_mul_f32_e32 v6, v6, v9
	v_cvt_pk_bf16_f32 v5, v5, v6
	global_store_dword v7, v5, s[44:45]
	v_mul_f32_e32 v5, v56, v1
	v_mul_f32_e32 v6, v57, v4
	v_cndmask_b32_e32 v9, v5, v6, vcc
	ds_bpermute_b32 v9, v212, v9
	s_waitcnt lgkmcnt(0)
	v_cndmask_b32_e32 v5, v9, v5, vcc
	v_cndmask_b32_e32 v6, v6, v9, vcc
	s_waitcnt vmcnt(31)
	v_lshlrev_b32_e32 v10, 16, v96
	v_and_b32_e32 v9, 0xffff0000, v96
	v_mul_f32_e32 v5, v5, v10
	v_mul_f32_e32 v6, v6, v9
	v_cvt_pk_bf16_f32 v5, v5, v6
	global_store_dword v7, v5, s[44:45] offset:64
	v_mul_f32_e32 v5, v40, v1
	v_mul_f32_e32 v6, v41, v4
	v_cndmask_b32_e32 v9, v5, v6, vcc
	ds_bpermute_b32 v9, v212, v9
	v_mul_f32_e32 v1, v24, v1
	v_mul_f32_e32 v4, v25, v4
	s_waitcnt lgkmcnt(0)
	v_cndmask_b32_e32 v5, v9, v5, vcc
	v_cndmask_b32_e32 v6, v6, v9, vcc
	s_waitcnt vmcnt(31)
	v_lshlrev_b32_e32 v10, 16, v97
	v_and_b32_e32 v9, 0xffff0000, v97
	v_mul_f32_e32 v5, v5, v10
	v_mul_f32_e32 v6, v6, v9
	v_cvt_pk_bf16_f32 v5, v5, v6
	global_store_dword v7, v5, s[44:45] offset:128
	v_cndmask_b32_e32 v5, v1, v4, vcc
	ds_bpermute_b32 v5, v212, v5
	s_waitcnt lgkmcnt(0)
	v_cndmask_b32_e32 v1, v5, v1, vcc
	v_cndmask_b32_e32 v4, v4, v5, vcc
	s_waitcnt vmcnt(31)
	v_lshlrev_b32_e32 v6, 16, v98
	v_and_b32_e32 v5, 0xffff0000, v98
	v_mul_f32_e32 v1, v1, v6
	v_mul_f32_e32 v4, v4, v5
	v_cvt_pk_bf16_f32 v1, v1, v4
	global_store_dword v7, v1, s[44:45] offset:192
	ds_read_b128 v[4:7], v8 offset:64
	s_waitcnt lgkmcnt(0)
	v_rcp_f32_e32 v1, v4
	v_rcp_f32_e32 v4, v5
	v_mul_f32_e32 v5, v74, v1
	v_mul_f32_e32 v9, v75, v4
	v_cndmask_b32_e32 v10, v5, v9, vcc
	ds_bpermute_b32 v10, v212, v10
	s_waitcnt lgkmcnt(0)
	v_cndmask_b32_e32 v5, v10, v5, vcc
	v_cndmask_b32_e32 v9, v9, v10, vcc
	v_or_b32_e32 v10, 0x10000, v2
	s_waitcnt vmcnt(31)
	v_lshlrev_b32_e32 v12, 16, v99
	v_and_b32_e32 v11, 0xffff0000, v99
	v_mul_f32_e32 v5, v5, v12
	v_mul_f32_e32 v9, v9, v11
	v_cvt_pk_bf16_f32 v5, v5, v9
	global_store_dword v10, v5, s[44:45]
	v_mul_f32_e32 v5, v58, v1
	v_mul_f32_e32 v9, v59, v4
	v_cndmask_b32_e32 v11, v5, v9, vcc
	ds_bpermute_b32 v11, v212, v11
	s_waitcnt lgkmcnt(0)
	v_cndmask_b32_e32 v5, v11, v5, vcc
	v_cndmask_b32_e32 v9, v9, v11, vcc
	s_waitcnt vmcnt(31)
	v_lshlrev_b32_e32 v12, 16, v100
	v_and_b32_e32 v11, 0xffff0000, v100
	v_mul_f32_e32 v5, v5, v12
	v_mul_f32_e32 v9, v9, v11
	v_cvt_pk_bf16_f32 v5, v5, v9
	global_store_dword v10, v5, s[44:45] offset:64
	v_mul_f32_e32 v5, v42, v1
	v_mul_f32_e32 v9, v43, v4
	v_cndmask_b32_e32 v11, v5, v9, vcc
	ds_bpermute_b32 v11, v212, v11
	v_mul_f32_e32 v1, v26, v1
	v_mul_f32_e32 v4, v27, v4
	s_waitcnt lgkmcnt(0)
	v_cndmask_b32_e32 v5, v11, v5, vcc
	v_cndmask_b32_e32 v9, v9, v11, vcc
	s_waitcnt vmcnt(31)
	v_lshlrev_b32_e32 v12, 16, v101
	v_and_b32_e32 v11, 0xffff0000, v101
	v_mul_f32_e32 v5, v5, v12
	v_mul_f32_e32 v9, v9, v11
	v_cvt_pk_bf16_f32 v5, v5, v9
	global_store_dword v10, v5, s[44:45] offset:128
	v_cndmask_b32_e32 v5, v1, v4, vcc
	ds_bpermute_b32 v5, v212, v5
	s_waitcnt lgkmcnt(0)
	v_cndmask_b32_e32 v1, v5, v1, vcc
	v_cndmask_b32_e32 v4, v4, v5, vcc
	s_waitcnt vmcnt(31)
	v_lshlrev_b32_e32 v9, 16, v102
	v_and_b32_e32 v5, 0xffff0000, v102
	v_mul_f32_e32 v1, v1, v9
	v_mul_f32_e32 v4, v4, v5
	v_cvt_pk_bf16_f32 v1, v1, v4
	global_store_dword v10, v1, s[44:45] offset:192
	v_rcp_f32_e32 v1, v6
	v_rcp_f32_e32 v4, v7
	v_mul_f32_e32 v5, v76, v1
	v_mul_f32_e32 v6, v77, v4
	v_cndmask_b32_e32 v7, v5, v6, vcc
	ds_bpermute_b32 v7, v212, v7
	s_waitcnt lgkmcnt(0)
	v_cndmask_b32_e32 v5, v7, v5, vcc
	v_cndmask_b32_e32 v6, v6, v7, vcc
	v_or_b32_e32 v7, 0x12000, v2
	s_waitcnt vmcnt(31)
	v_lshlrev_b32_e32 v10, 16, v103
	v_and_b32_e32 v9, 0xffff0000, v103
	v_mul_f32_e32 v5, v5, v10
	v_mul_f32_e32 v6, v6, v9
	v_cvt_pk_bf16_f32 v5, v5, v6
	global_store_dword v7, v5, s[44:45]
	v_mul_f32_e32 v5, v60, v1
	v_mul_f32_e32 v6, v61, v4
	v_cndmask_b32_e32 v9, v5, v6, vcc
	ds_bpermute_b32 v9, v212, v9
	s_waitcnt lgkmcnt(0)
	v_cndmask_b32_e32 v5, v9, v5, vcc
	v_cndmask_b32_e32 v6, v6, v9, vcc
	s_waitcnt vmcnt(31)
	v_lshlrev_b32_e32 v10, 16, v104
	v_and_b32_e32 v9, 0xffff0000, v104
	v_mul_f32_e32 v5, v5, v10
	v_mul_f32_e32 v6, v6, v9
	v_cvt_pk_bf16_f32 v5, v5, v6
	global_store_dword v7, v5, s[44:45] offset:64
	v_mul_f32_e32 v5, v44, v1
	v_mul_f32_e32 v6, v45, v4
	v_cndmask_b32_e32 v9, v5, v6, vcc
	ds_bpermute_b32 v9, v212, v9
	v_mul_f32_e32 v1, v28, v1
	v_mul_f32_e32 v4, v29, v4
	s_waitcnt lgkmcnt(0)
	v_cndmask_b32_e32 v5, v9, v5, vcc
	v_cndmask_b32_e32 v6, v6, v9, vcc
	s_waitcnt vmcnt(31)
	v_lshlrev_b32_e32 v10, 16, v105
	v_and_b32_e32 v9, 0xffff0000, v105
	v_mul_f32_e32 v5, v5, v10
	v_mul_f32_e32 v6, v6, v9
	v_cvt_pk_bf16_f32 v5, v5, v6
	global_store_dword v7, v5, s[44:45] offset:128
	v_cndmask_b32_e32 v5, v1, v4, vcc
	ds_bpermute_b32 v5, v212, v5
	s_waitcnt lgkmcnt(0)
	v_cndmask_b32_e32 v1, v5, v1, vcc
	v_cndmask_b32_e32 v4, v4, v5, vcc
	s_waitcnt vmcnt(31)
	v_lshlrev_b32_e32 v6, 16, v106
	v_and_b32_e32 v5, 0xffff0000, v106
	v_mul_f32_e32 v1, v1, v6
	v_mul_f32_e32 v4, v4, v5
	v_cvt_pk_bf16_f32 v1, v1, v4
	global_store_dword v7, v1, s[44:45] offset:192
	ds_read_b128 v[4:7], v8 offset:96
	s_waitcnt lgkmcnt(0)
	v_rcp_f32_e32 v4, v4
	v_rcp_f32_e32 v5, v5
	v_mul_f32_e32 v1, v78, v4
	v_mul_f32_e32 v8, v79, v5
	v_cndmask_b32_e32 v9, v1, v8, vcc
	ds_bpermute_b32 v9, v212, v9
	s_waitcnt lgkmcnt(0)
	v_cndmask_b32_e32 v1, v9, v1, vcc
	v_cndmask_b32_e32 v8, v8, v9, vcc
	v_or_b32_e32 v9, 0x18000, v2
	v_or_b32_e32 v2, 0x1a000, v2
	s_waitcnt vmcnt(31)
	v_lshlrev_b32_e32 v11, 16, v107
	v_and_b32_e32 v10, 0xffff0000, v107
	v_mul_f32_e32 v1, v1, v11
	v_mul_f32_e32 v8, v8, v10
	v_cvt_pk_bf16_f32 v1, v1, v8
	global_store_dword v9, v1, s[44:45]
	v_mul_f32_e32 v1, v62, v4
	v_mul_f32_e32 v8, v63, v5
	v_cndmask_b32_e32 v10, v1, v8, vcc
	ds_bpermute_b32 v10, v212, v10
	s_waitcnt lgkmcnt(0)
	v_cndmask_b32_e32 v1, v10, v1, vcc
	v_cndmask_b32_e32 v8, v8, v10, vcc
	s_waitcnt vmcnt(31)
	v_lshlrev_b32_e32 v11, 16, v108
	v_and_b32_e32 v10, 0xffff0000, v108
	v_mul_f32_e32 v1, v1, v11
	v_mul_f32_e32 v8, v8, v10
	v_cvt_pk_bf16_f32 v1, v1, v8
	global_store_dword v9, v1, s[44:45] offset:64
	v_mul_f32_e32 v1, v46, v4
	v_mul_f32_e32 v8, v47, v5
	v_cndmask_b32_e32 v10, v1, v8, vcc
	ds_bpermute_b32 v10, v212, v10
	s_waitcnt lgkmcnt(0)
	v_cndmask_b32_e32 v1, v10, v1, vcc
	v_cndmask_b32_e32 v8, v8, v10, vcc
	s_waitcnt vmcnt(31)
	v_lshlrev_b32_e32 v11, 16, v109
	v_and_b32_e32 v10, 0xffff0000, v109
	v_mul_f32_e32 v1, v1, v11
	v_mul_f32_e32 v8, v8, v10
	v_cvt_pk_bf16_f32 v1, v1, v8
	global_store_dword v9, v1, s[44:45] offset:128
	v_mul_f32_e32 v1, v30, v4
	v_mul_f32_e32 v4, v31, v5
	v_cndmask_b32_e32 v5, v1, v4, vcc
	ds_bpermute_b32 v5, v212, v5
	s_waitcnt lgkmcnt(0)
	v_cndmask_b32_e32 v1, v5, v1, vcc
	v_cndmask_b32_e32 v4, v4, v5, vcc
	s_waitcnt vmcnt(31)
	v_lshlrev_b32_e32 v8, 16, v110
	v_and_b32_e32 v5, 0xffff0000, v110
	v_mul_f32_e32 v1, v1, v8
	v_mul_f32_e32 v4, v4, v5
	v_cvt_pk_bf16_f32 v1, v1, v4
	global_store_dword v9, v1, s[44:45] offset:192
	v_rcp_f32_e32 v1, v6
	v_rcp_f32_e32 v4, v7
	v_mul_f32_e32 v5, v80, v1
	v_mul_f32_e32 v6, v81, v4
	v_cndmask_b32_e32 v7, v5, v6, vcc
	ds_bpermute_b32 v7, v212, v7
	s_waitcnt lgkmcnt(0)
	v_cndmask_b32_e32 v5, v7, v5, vcc
	v_cndmask_b32_e32 v6, v6, v7, vcc
	s_waitcnt vmcnt(31)
	v_lshlrev_b32_e32 v8, 16, v111
	v_and_b32_e32 v7, 0xffff0000, v111
	v_mul_f32_e32 v5, v5, v8
	v_mul_f32_e32 v6, v6, v7
	v_cvt_pk_bf16_f32 v5, v5, v6
	global_store_dword v2, v5, s[44:45]
	v_mul_f32_e32 v5, v64, v1
	v_mul_f32_e32 v6, v65, v4
	v_cndmask_b32_e32 v7, v5, v6, vcc
	ds_bpermute_b32 v7, v212, v7
	s_waitcnt lgkmcnt(0)
	v_cndmask_b32_e32 v5, v7, v5, vcc
	v_cndmask_b32_e32 v6, v6, v7, vcc
	s_waitcnt vmcnt(31)
	v_lshlrev_b32_e32 v8, 16, v112
	v_and_b32_e32 v7, 0xffff0000, v112
	v_mul_f32_e32 v5, v5, v8
	v_mul_f32_e32 v6, v6, v7
	v_cvt_pk_bf16_f32 v5, v5, v6
	global_store_dword v2, v5, s[44:45] offset:64
	v_mul_f32_e32 v5, v48, v1
	v_mul_f32_e32 v6, v49, v4
	v_cndmask_b32_e32 v7, v5, v6, vcc
	ds_bpermute_b32 v7, v212, v7
	v_mul_f32_e32 v1, v32, v1
	v_mul_f32_e32 v4, v33, v4
	s_waitcnt lgkmcnt(0)
	v_cndmask_b32_e32 v5, v7, v5, vcc
	v_cndmask_b32_e32 v6, v6, v7, vcc
	s_waitcnt vmcnt(31)
	v_lshlrev_b32_e32 v8, 16, v113
	v_and_b32_e32 v7, 0xffff0000, v113
	v_mul_f32_e32 v5, v5, v8
	v_mul_f32_e32 v6, v6, v7
	v_cvt_pk_bf16_f32 v5, v5, v6
	global_store_dword v2, v5, s[44:45] offset:128
	v_cndmask_b32_e32 v5, v1, v4, vcc
	ds_bpermute_b32 v5, v212, v5
	s_waitcnt lgkmcnt(0)
	v_cndmask_b32_e32 v1, v5, v1, vcc
	v_cndmask_b32_e32 v4, v4, v5, vcc
	s_waitcnt vmcnt(31)
	v_lshlrev_b32_e32 v6, 16, v114
	v_and_b32_e32 v5, 0xffff0000, v114
	v_mul_f32_e32 v1, v1, v6
	v_mul_f32_e32 v4, v4, v5
	v_cvt_pk_bf16_f32 v1, v1, v4
	global_store_dword v2, v1, s[44:45] offset:192
	s_mov_b64 s[44:45], 0
